# loop-edge/interleave tuning: 12 v_exp (instead of 8) between the post-barrier K ds_reads and the first QK MFMA in BAR steps
# baseline (speedup 1.0000x reference)
.LBB0_641:
	s_add_i32 s24, s23, -7
	s_lshl_b32 s92, s24, 13
	s_add_u32 vcc_lo, s100, s92
	s_addc_u32 vcc_hi, s101, 0
	global_load_dwordx4 v[52:55], v248, vcc
	s_add_i32 s24, s23, -8
	s_lshl_b32 s92, s24, 7
	s_add_u32 vcc_lo, s98, s92
	s_addc_u32 vcc_hi, s99, 0
	global_load_dwordx4 v[56:59], v249, vcc
	s_mul_i32 s26, s25, 0x2400
	s_add_i32 s24, s23, -7
	s_add_i32 s27, s26, 0xffffdc00
	s_cmp_lg_u32 s25, 0
	s_cselect_b32 s27, s27, 0x9000
	v_add_u32_e32 v1, s27, v163
	ds_read_b128 v[60:63], v1 offset:36864
	ds_read_b128 v[114:117], v1 offset:36896
	ds_read_b128 v[118:121], v1 offset:41472
	ds_read_b128 v[134:137], v1 offset:41504
	ds_read_b128 v[146:149], v1 offset:36928
	ds_read_b128 v[150:153], v1 offset:36960
	ds_read_b128 v[196:199], v1 offset:41536
	ds_read_b128 v[200:203], v1 offset:41568
	s_setprio 3
	v_cvt_pk_bf16_f32 v204, v102, v103
	v_cvt_pk_bf16_f32 v205, v104, v105
	v_cvt_pk_bf16_f32 v206, v98, v99
	v_cvt_pk_bf16_f32 v207, v100, v101
	s_waitcnt lgkmcnt(7)
	s_nop 0
	v_mfma_f32_32x32x16_bf16 v[18:33], v[60:63], v[204:207], v[18:33]
	v_add_f32_e32 v1, v102, v103
	v_add_f32_e32 v1, v1, v104
	v_add_f32_e32 v1, v1, v105
	s_waitcnt lgkmcnt(5)
	v_mfma_f32_32x32x16_bf16 v[2:17], v[118:121], v[204:207], v[2:17]
	v_cvt_pk_bf16_f32 v60, v194, v187
	v_cvt_pk_bf16_f32 v61, v186, v185
	v_cvt_pk_bf16_f32 v62, v133, v132
	v_cvt_pk_bf16_f32 v63, v131, v130
	v_add_f32_e32 v1, v1, v98
	v_add_f32_e32 v1, v1, v99
	v_add_f32_e32 v1, v1, v100
	v_add_f32_e32 v1, v1, v101
	s_nop 0
	v_mfma_f32_32x32x16_bf16 v[18:33], v[114:117], v[60:63], v[18:33]
	v_add_f32_e32 v1, v1, v194
	v_add_f32_e32 v1, v1, v187
	v_add_f32_e32 v1, v1, v186
	v_add_f32_e32 v1, v1, v185
	s_waitcnt lgkmcnt(4)
	v_mfma_f32_32x32x16_bf16 v[2:17], v[134:137], v[60:63], v[2:17]
	v_cvt_pk_bf16_f32 v98, v129, v128
	v_cvt_pk_bf16_f32 v99, v127, v126
	v_cvt_pk_bf16_f32 v100, v125, v124
	v_cvt_pk_bf16_f32 v101, v123, v122
	v_add_f32_e32 v1, v1, v133
	v_add_f32_e32 v1, v1, v132
	v_add_f32_e32 v1, v1, v131
	v_add_f32_e32 v1, v1, v130
	s_waitcnt lgkmcnt(3)
	v_mfma_f32_32x32x16_bf16 v[18:33], v[146:149], v[98:101], v[18:33]
	v_add_f32_e32 v1, v1, v129
	v_add_f32_e32 v1, v1, v128
	v_add_f32_e32 v1, v1, v127
	v_add_f32_e32 v1, v1, v126
	s_waitcnt lgkmcnt(1)
	v_mfma_f32_32x32x16_bf16 v[2:17], v[196:199], v[98:101], v[2:17]
	v_cvt_pk_bf16_f32 v60, v109, v108
	v_cvt_pk_bf16_f32 v61, v107, v106
	v_cvt_pk_bf16_f32 v62, v113, v112
	v_cvt_pk_bf16_f32 v63, v111, v110
	v_add_f32_e32 v1, v1, v125
	v_add_f32_e32 v1, v1, v124
	v_add_f32_e32 v1, v1, v123
	v_add_f32_e32 v1, v1, v122
	s_nop 0
	v_mfma_f32_32x32x16_bf16 v[18:33], v[150:153], v[60:63], v[18:33]
	v_add_f32_e32 v1, v1, v109
	v_add_f32_e32 v1, v1, v108
	v_add_f32_e32 v1, v1, v107
	v_add_f32_e32 v1, v1, v106
	s_waitcnt lgkmcnt(0)
	v_mfma_f32_32x32x16_bf16 v[2:17], v[200:203], v[60:63], v[2:17]
	v_add_f32_e32 v1, v1, v113
	v_add_f32_e32 v1, v1, v112
	v_add_f32_e32 v1, v1, v111
	v_add_f32_e32 v1, v1, v110
	s_setprio 2
	s_waitcnt lgkmcnt(0)
	s_barrier
	ds_read_b128 v[240:243], v165 offset:18432
	ds_read_b128 v[244:247], v165 offset:23040
	ds_read_b128 v[130:133], v165 offset:18464
	ds_read_b128 v[146:149], v165 offset:23072
	v_exp_f32_e32 v185, v82
	v_exp_f32_e32 v186, v83
	v_exp_f32_e32 v187, v84
	v_exp_f32_e32 v194, v85
	v_exp_f32_e32 v195, v86
	v_exp_f32_e32 v196, v87
	v_exp_f32_e32 v197, v88
	v_exp_f32_e32 v198, v89
	v_exp_f32_e32 v199, v90
	v_exp_f32_e32 v200, v91
	v_exp_f32_e32 v201, v92
	v_exp_f32_e32 v202, v93
	s_waitcnt lgkmcnt(2)
	v_mfma_f32_32x32x16_bf16 v[114:129], v[240:243], v[158:161], v[34:49]
	s_waitcnt lgkmcnt(1)
	v_mfma_f32_32x32x16_bf16 v[98:113], v[244:247], v[158:161], v[34:49]
	v_exp_f32_e32 v134, v94
	v_exp_f32_e32 v135, v95
	v_exp_f32_e32 v136, v96
	v_exp_f32_e32 v137, v97
	v_mfma_f32_32x32x16_bf16 v[114:129], v[130:133], v[154:157], v[114:129]
	v_exp_f32_e32 v96, v66
	v_exp_f32_e32 v97, v67
	v_exp_f32_e32 v203, v68
	v_exp_f32_e32 v204, v69
	v_exp_f32_e32 v130, v70
	v_exp_f32_e32 v131, v71
	v_exp_f32_e32 v132, v72
	v_exp_f32_e32 v133, v73
	s_waitcnt lgkmcnt(0)
	v_mfma_f32_32x32x16_bf16 v[98:113], v[146:149], v[154:157], v[98:113]
	v_exp_f32_e32 v205, v74
	v_exp_f32_e32 v206, v75
	v_exp_f32_e32 v207, v76
	v_exp_f32_e32 v208, v77
	v_exp_f32_e32 v209, v78
	v_exp_f32_e32 v210, v79
	v_exp_f32_e32 v211, v80
	v_exp_f32_e32 v212, v81
	v_add_u32_e32 v88, s26, v163
	ds_read_b128 v[240:243], v165 offset:27648
	ds_read_b128 v[244:247], v165 offset:32256
	ds_read_b128 v[60:63], v88 offset:41472
	ds_read_b128 v[64:67], v88 offset:36864
	ds_read_b128 v[68:71], v88 offset:36896
	ds_read_b128 v[72:75], v88 offset:41504
	ds_read_b128 v[76:79], v88 offset:36928
	ds_read_b128 v[80:83], v88 offset:41536
	ds_read_b128 v[84:87], v88 offset:36960
	ds_read_b128 v[88:91], v88 offset:41568
	s_cmp_gt_i32 s25, 2
	s_cselect_b32 s27, -3, 2
	s_add_i32 s27, s27, s25
	s_add_i32 s26, s23, -6
	s_mulk_i32 s27, 0x2400
	s_min_u32 s26, s26, s13
	v_add_u32_e32 v51, s27, v182
	s_min_u32 s24, s24, s13
	s_lshl_b32 s92, s26, 13
	s_waitcnt vmcnt(3)
	ds_write_b128 v182, v[138:141]
	s_waitcnt vmcnt(2)
	ds_write_b128 v51, v[142:145] offset:36864
	v_add_f32_e32 v1, v50, v1
	s_add_u32 vcc_lo, s100, s92
	s_addc_u32 vcc_hi, s101, 0
	global_load_dwordx4 v[146:149], v248, vcc
	s_lshl_b32 s92, s24, 7
	s_add_u32 vcc_lo, s98, s92
	s_addc_u32 vcc_hi, s99, 0
	global_load_dwordx4 v[150:153], v249, vcc
	s_add_i32 s27, s25, 1
	s_setprio 1
	v_cvt_pk_bf16_f32 v92, v185, v186
	v_cvt_pk_bf16_f32 v93, v187, v194
	v_cvt_pk_bf16_f32 v94, v195, v196
	v_cvt_pk_bf16_f32 v95, v197, v198
	s_waitcnt lgkmcnt(8)
	s_nop 0
	v_mfma_f32_32x32x16_bf16 v[18:33], v[64:67], v[92:95], v[18:33]
	v_add_f32_e32 v213, v185, v186
	v_add_f32_e32 v213, v213, v187
	v_add_f32_e32 v213, v213, v194
	s_nop 0
	v_mfma_f32_32x32x16_bf16 v[2:17], v[60:63], v[92:95], v[2:17]
	v_cvt_pk_bf16_f32 v64, v199, v200
	v_cvt_pk_bf16_f32 v65, v201, v202
	v_cvt_pk_bf16_f32 v66, v134, v135
	v_cvt_pk_bf16_f32 v67, v136, v137
	v_add_f32_e32 v213, v213, v195
	v_add_f32_e32 v213, v213, v196
	v_add_f32_e32 v213, v213, v197
	v_add_f32_e32 v213, v213, v198
	s_waitcnt lgkmcnt(7)
	v_mfma_f32_32x32x16_bf16 v[18:33], v[68:71], v[64:67], v[18:33]
	v_add_f32_e32 v213, v213, v199
	v_add_f32_e32 v213, v213, v200
	v_add_f32_e32 v213, v213, v201
	v_add_f32_e32 v213, v213, v202
	s_waitcnt lgkmcnt(6)
	v_mfma_f32_32x32x16_bf16 v[2:17], v[72:75], v[64:67], v[2:17]
	v_cvt_pk_bf16_f32 v60, v96, v97
	v_cvt_pk_bf16_f32 v61, v203, v204
	v_cvt_pk_bf16_f32 v62, v130, v131
	v_cvt_pk_bf16_f32 v63, v132, v133
	v_add_f32_e32 v213, v213, v134
	v_add_f32_e32 v213, v213, v135
	v_add_f32_e32 v213, v213, v136
	v_add_f32_e32 v213, v213, v137
	s_waitcnt lgkmcnt(5)
	v_mfma_f32_32x32x16_bf16 v[18:33], v[76:79], v[60:63], v[18:33]
	v_add_f32_e32 v213, v213, v96
	v_add_f32_e32 v213, v213, v97
	v_add_f32_e32 v213, v213, v203
	v_add_f32_e32 v213, v213, v204
	s_waitcnt lgkmcnt(4)
	v_mfma_f32_32x32x16_bf16 v[2:17], v[80:83], v[60:63], v[2:17]
	v_cvt_pk_bf16_f32 v64, v205, v206
	v_cvt_pk_bf16_f32 v65, v207, v208
	v_cvt_pk_bf16_f32 v66, v209, v210
	v_cvt_pk_bf16_f32 v67, v211, v212
	v_add_f32_e32 v213, v213, v130
	v_add_f32_e32 v213, v213, v131
	v_add_f32_e32 v213, v213, v132
	v_add_f32_e32 v213, v213, v133
	s_waitcnt lgkmcnt(3)
	v_mfma_f32_32x32x16_bf16 v[18:33], v[84:87], v[64:67], v[18:33]
	v_add_f32_e32 v213, v213, v205
	v_add_f32_e32 v213, v213, v206
	v_add_f32_e32 v213, v213, v207
	v_add_f32_e32 v213, v213, v208
	s_waitcnt lgkmcnt(2)
	v_mfma_f32_32x32x16_bf16 v[2:17], v[88:91], v[64:67], v[2:17]
	v_add_f32_e32 v213, v213, v209
	v_add_f32_e32 v213, v213, v210
	v_add_f32_e32 v213, v213, v211
	v_add_f32_e32 v213, v213, v212
	s_setprio 0
	ds_read_b128 v[64:67], v165 offset:27680
	ds_read_b128 v[72:75], v165 offset:32288
	s_cmp_lg_u32 s25, 4
	s_cselect_b32 s24, s27, 0
	s_waitcnt lgkmcnt(2)
	v_mfma_f32_32x32x16_bf16 v[130:145], v[240:243], v[158:161], v[34:49]
	v_exp_f32_e32 v185, v114
	v_exp_f32_e32 v186, v115
	v_exp_f32_e32 v187, v116
	v_exp_f32_e32 v194, v117
	v_exp_f32_e32 v195, v118
	v_exp_f32_e32 v196, v119
	v_exp_f32_e32 v197, v120
	v_exp_f32_e32 v198, v121
	s_waitcnt lgkmcnt(1)
	v_mfma_f32_32x32x16_bf16 v[82:97], v[244:247], v[158:161], v[34:49]
	v_exp_f32_e32 v199, v122
	v_exp_f32_e32 v200, v123
	v_exp_f32_e32 v201, v124
	v_exp_f32_e32 v202, v125
	v_exp_f32_e32 v122, v126
	v_exp_f32_e32 v123, v127
	v_exp_f32_e32 v124, v128
	v_exp_f32_e32 v125, v129
	v_mfma_f32_32x32x16_bf16 v[130:145], v[64:67], v[154:157], v[130:145]
	v_exp_f32_e32 v126, v98
	v_exp_f32_e32 v127, v99
	v_exp_f32_e32 v128, v100
	v_exp_f32_e32 v129, v101
	v_exp_f32_e32 v203, v102
	v_exp_f32_e32 v204, v103
	v_exp_f32_e32 v205, v104
	v_exp_f32_e32 v206, v105
	s_waitcnt lgkmcnt(0)
	v_mfma_f32_32x32x16_bf16 v[82:97], v[72:75], v[154:157], v[82:97]
	v_exp_f32_e32 v102, v106
	v_exp_f32_e32 v103, v107
	v_exp_f32_e32 v104, v108
	v_exp_f32_e32 v105, v109
	v_exp_f32_e32 v106, v110
	v_exp_f32_e32 v107, v111
	v_exp_f32_e32 v108, v112
	v_exp_f32_e32 v109, v113
	s_cmp_gt_i32 s24, 2
	s_cselect_b32 s25, -3, 2
	s_add_i32 s25, s25, s24
	s_mulk_i32 s25, 0x2400
	v_add_u32_e32 v50, s25, v182
	s_add_i32 s25, s24, 1
	s_cmp_lg_u32 s24, 4
	s_cselect_b32 s24, s25, 0
	s_add_i32 s25, s23, -5
	s_min_u32 s25, s25, s13
	s_lshl_b32 s92, s25, 13
	s_waitcnt vmcnt(3)
	ds_write_b128 v182, v[52:55] offset:9216
	s_waitcnt vmcnt(2)
	ds_write_b128 v50, v[56:59] offset:36864
	s_add_u32 vcc_lo, s100, s92
	s_addc_u32 vcc_hi, s101, 0
	global_load_dwordx4 v[118:121], v248, vcc
	s_lshl_b32 s92, s26, 7
	s_add_u32 vcc_lo, s98, s92
	s_addc_u32 vcc_hi, s99, 0
	global_load_dwordx4 v[114:117], v249, vcc
	s_mul_i32 s26, s24, 0x2400
	s_add_i32 s27, s26, 0xffffdc00
	s_cmp_lg_u32 s24, 0
	s_cselect_b32 s27, s27, 0x9000
	v_add_u32_e32 v78, s27, v163
	ds_read_b128 v[50:53], v78 offset:36864
	ds_read_b128 v[54:57], v78 offset:36896
	ds_read_b128 v[58:61], v78 offset:41472
	ds_read_b128 v[62:65], v78 offset:41504
	ds_read_b128 v[66:69], v78 offset:36928
	ds_read_b128 v[70:73], v78 offset:36960
	ds_read_b128 v[74:77], v78 offset:41536
	ds_read_b128 v[78:81], v78 offset:41568
	s_setprio 3
	v_cvt_pk_bf16_f32 v98, v185, v186
	v_cvt_pk_bf16_f32 v99, v187, v194
	v_cvt_pk_bf16_f32 v100, v195, v196
	v_cvt_pk_bf16_f32 v101, v197, v198
	s_waitcnt lgkmcnt(7)
	s_nop 0
	v_mfma_f32_32x32x16_bf16 v[18:33], v[50:53], v[98:101], v[18:33]
	v_add_f32_e32 v110, v185, v186
	v_add_f32_e32 v110, v110, v187
	v_add_f32_e32 v110, v110, v194
	s_waitcnt lgkmcnt(5)
	v_mfma_f32_32x32x16_bf16 v[2:17], v[58:61], v[98:101], v[2:17]
	v_cvt_pk_bf16_f32 v50, v199, v200
	v_cvt_pk_bf16_f32 v51, v201, v202
	v_cvt_pk_bf16_f32 v52, v122, v123
	v_cvt_pk_bf16_f32 v53, v124, v125
	v_add_f32_e32 v110, v110, v195
	v_add_f32_e32 v110, v110, v196
	v_add_f32_e32 v110, v110, v197
	v_add_f32_e32 v110, v110, v198
	s_nop 0
	v_mfma_f32_32x32x16_bf16 v[18:33], v[54:57], v[50:53], v[18:33]
	v_add_f32_e32 v110, v110, v199
	v_add_f32_e32 v110, v110, v200
	v_add_f32_e32 v110, v110, v201
	v_add_f32_e32 v110, v110, v202
	s_waitcnt lgkmcnt(4)
	v_mfma_f32_32x32x16_bf16 v[2:17], v[62:65], v[50:53], v[2:17]
	v_cvt_pk_bf16_f32 v54, v126, v127
	v_cvt_pk_bf16_f32 v55, v128, v129
	v_cvt_pk_bf16_f32 v56, v203, v204
	v_cvt_pk_bf16_f32 v57, v205, v206
	v_add_f32_e32 v110, v110, v122
	v_add_f32_e32 v110, v110, v123
	v_add_f32_e32 v110, v110, v124
	v_add_f32_e32 v110, v110, v125
	s_waitcnt lgkmcnt(3)
	v_mfma_f32_32x32x16_bf16 v[18:33], v[66:69], v[54:57], v[18:33]
	v_add_f32_e32 v110, v110, v126
	v_add_f32_e32 v110, v110, v127
	v_add_f32_e32 v110, v110, v128
	v_add_f32_e32 v110, v110, v129
	s_waitcnt lgkmcnt(1)
	v_mfma_f32_32x32x16_bf16 v[2:17], v[74:77], v[54:57], v[2:17]
	v_cvt_pk_bf16_f32 v50, v102, v103
	v_cvt_pk_bf16_f32 v51, v104, v105
	v_cvt_pk_bf16_f32 v52, v106, v107
	v_cvt_pk_bf16_f32 v53, v108, v109
	v_add_f32_e32 v110, v110, v203
	v_add_f32_e32 v110, v110, v204
	v_add_f32_e32 v110, v110, v205
	v_add_f32_e32 v110, v110, v206
	s_nop 0
	v_mfma_f32_32x32x16_bf16 v[18:33], v[70:73], v[50:53], v[18:33]
	v_add_f32_e32 v110, v110, v102
	v_add_f32_e32 v110, v110, v103
	v_add_f32_e32 v110, v110, v104
	v_add_f32_e32 v110, v110, v105
	s_waitcnt lgkmcnt(0)
	v_mfma_f32_32x32x16_bf16 v[2:17], v[78:81], v[50:53], v[2:17]
	v_add_f32_e32 v110, v110, v106
	v_add_f32_e32 v110, v110, v107
	v_add_f32_e32 v110, v110, v108
	v_add_f32_e32 v110, v110, v109
	s_setprio 2
	s_waitcnt lgkmcnt(0)
	s_barrier
	ds_read_b128 v[240:243], v165
	ds_read_b128 v[244:247], v165 offset:4608
	ds_read_b128 v[102:105], v165 offset:32
	ds_read_b128 v[106:109], v165 offset:4640
	v_add_f32_e32 v1, v1, v213
	v_exp_f32_e32 v185, v130
	v_exp_f32_e32 v186, v131
	v_exp_f32_e32 v187, v132
	v_exp_f32_e32 v194, v133
	v_exp_f32_e32 v195, v134
	v_exp_f32_e32 v196, v135
	v_exp_f32_e32 v197, v136
	v_exp_f32_e32 v198, v137
	v_exp_f32_e32 v134, v138
	v_exp_f32_e32 v135, v139
	v_exp_f32_e32 v136, v140
	v_exp_f32_e32 v137, v141
	s_waitcnt lgkmcnt(2)
	v_mfma_f32_32x32x16_bf16 v[66:81], v[240:243], v[158:161], v[34:49]
	v_mfma_f32_32x32x16_bf16 v[50:65], v[244:247], v[158:161], v[34:49]
	v_exp_f32_e32 v138, v142
	v_exp_f32_e32 v139, v143
	v_exp_f32_e32 v140, v144
	v_exp_f32_e32 v141, v145
	s_waitcnt lgkmcnt(1)
	v_mfma_f32_32x32x16_bf16 v[66:81], v[102:105], v[154:157], v[66:81]
	v_exp_f32_e32 v142, v82
	v_exp_f32_e32 v143, v83
	v_exp_f32_e32 v144, v84
	v_exp_f32_e32 v145, v85
	v_exp_f32_e32 v199, v86
	v_exp_f32_e32 v200, v87
	v_exp_f32_e32 v201, v88
	v_exp_f32_e32 v202, v89
	s_waitcnt lgkmcnt(0)
	v_mfma_f32_32x32x16_bf16 v[50:65], v[106:109], v[154:157], v[50:65]
	v_exp_f32_e32 v203, v90
	v_exp_f32_e32 v204, v91
	v_exp_f32_e32 v205, v92
	v_exp_f32_e32 v206, v93
	v_exp_f32_e32 v207, v94
	v_exp_f32_e32 v208, v95
	v_exp_f32_e32 v209, v96
	v_exp_f32_e32 v210, v97
	v_add_f32_e32 v1, v1, v110
	v_add_u32_e32 v111, s26, v163
	ds_read_b128 v[240:243], v165 offset:9216
	ds_read_b128 v[244:247], v165 offset:13824
	ds_read_b128 v[82:85], v111 offset:41472
	ds_read_b128 v[86:89], v111 offset:36864
	ds_read_b128 v[90:93], v111 offset:36896
	ds_read_b128 v[94:97], v111 offset:41504
	ds_read_b128 v[98:101], v111 offset:36928
	ds_read_b128 v[102:105], v111 offset:41536
	ds_read_b128 v[106:109], v111 offset:36960
	ds_read_b128 v[110:113], v111 offset:41568
	s_cmp_gt_i32 s24, 2
	s_cselect_b32 s27, -3, 2
	s_add_i32 s27, s27, s24
	s_mulk_i32 s27, 0x2400
	v_add_u32_e32 v250, s27, v182
	s_mov_b32 s27, 0x18950000
	s_waitcnt vmcnt(3)
	ds_write_b128 v182, v[146:149] offset:18432
	s_waitcnt vmcnt(2)
	ds_write_b128 v250, v[150:153] offset:36864
	s_add_i32 s92, s23, -4
	s_lshl_b32 s92, s92, 13
	s_add_u32 vcc_lo, s100, s92
	s_addc_u32 vcc_hi, s101, 0
	global_load_dwordx4 v[126:129], v248, vcc
	s_lshl_b32 s92, s25, 7
	s_add_u32 vcc_lo, s98, s92
	s_addc_u32 vcc_hi, s99, 0
	global_load_dwordx4 v[122:125], v249, vcc
	s_add_i32 s26, s24, 1
	s_setprio 1
	v_cvt_pk_bf16_f32 v130, v185, v186
	v_cvt_pk_bf16_f32 v131, v187, v194
	v_cvt_pk_bf16_f32 v132, v195, v196
	v_cvt_pk_bf16_f32 v133, v197, v198
	s_waitcnt lgkmcnt(8)
	s_nop 0
	v_mfma_f32_32x32x16_bf16 v[18:33], v[86:89], v[130:133], v[18:33]
	v_add_f32_e32 v146, v185, v186
	v_add_f32_e32 v146, v146, v187
	v_add_f32_e32 v146, v146, v194
	s_nop 0
	v_mfma_f32_32x32x16_bf16 v[2:17], v[82:85], v[130:133], v[2:17]
	v_cvt_pk_bf16_f32 v86, v134, v135
	v_cvt_pk_bf16_f32 v87, v136, v137
	v_cvt_pk_bf16_f32 v88, v138, v139
	v_cvt_pk_bf16_f32 v89, v140, v141
	v_add_f32_e32 v146, v146, v195
	v_add_f32_e32 v146, v146, v196
	v_add_f32_e32 v146, v146, v197
	v_add_f32_e32 v146, v146, v198
	s_waitcnt lgkmcnt(7)
	v_mfma_f32_32x32x16_bf16 v[18:33], v[90:93], v[86:89], v[18:33]
	v_add_f32_e32 v146, v146, v134
	v_add_f32_e32 v146, v146, v135
	v_add_f32_e32 v146, v146, v136
	v_add_f32_e32 v146, v146, v137
	s_waitcnt lgkmcnt(6)
	v_mfma_f32_32x32x16_bf16 v[2:17], v[94:97], v[86:89], v[2:17]
	v_cvt_pk_bf16_f32 v82, v142, v143
	v_cvt_pk_bf16_f32 v83, v144, v145
	v_cvt_pk_bf16_f32 v84, v199, v200
	v_cvt_pk_bf16_f32 v85, v201, v202
	v_add_f32_e32 v146, v146, v138
	v_add_f32_e32 v146, v146, v139
	v_add_f32_e32 v146, v146, v140
	v_add_f32_e32 v146, v146, v141
	s_waitcnt lgkmcnt(5)
	v_mfma_f32_32x32x16_bf16 v[18:33], v[98:101], v[82:85], v[18:33]
	v_add_f32_e32 v146, v146, v142
	v_add_f32_e32 v146, v146, v143
	v_add_f32_e32 v146, v146, v144
	v_add_f32_e32 v146, v146, v145
	s_waitcnt lgkmcnt(4)
	v_mfma_f32_32x32x16_bf16 v[2:17], v[102:105], v[82:85], v[2:17]
	v_cvt_pk_bf16_f32 v86, v203, v204
	v_cvt_pk_bf16_f32 v87, v205, v206
	v_cvt_pk_bf16_f32 v88, v207, v208
	v_cvt_pk_bf16_f32 v89, v209, v210
	v_add_f32_e32 v146, v146, v199
	v_add_f32_e32 v146, v146, v200
	v_add_f32_e32 v146, v146, v201
	v_add_f32_e32 v146, v146, v202
	s_waitcnt lgkmcnt(3)
	v_mfma_f32_32x32x16_bf16 v[18:33], v[106:109], v[86:89], v[18:33]
	v_add_f32_e32 v146, v146, v203
	v_add_f32_e32 v146, v146, v204
	v_add_f32_e32 v146, v146, v205
	v_add_f32_e32 v146, v146, v206
	s_waitcnt lgkmcnt(2)
	v_mfma_f32_32x32x16_bf16 v[2:17], v[110:113], v[86:89], v[2:17]
	v_add_f32_e32 v146, v146, v207
	v_add_f32_e32 v146, v146, v208
	v_add_f32_e32 v146, v146, v209
	v_add_f32_e32 v146, v146, v210
	s_setprio 0
	ds_read_b128 v[130:133], v165 offset:9248
	ds_read_b128 v[138:141], v165 offset:13856
	s_cmp_lg_u32 s24, 4
	s_cselect_b32 s24, s26, 0
	s_waitcnt lgkmcnt(2)
	v_mfma_f32_32x32x16_bf16 v[98:113], v[240:243], v[158:161], v[34:49]
	v_exp_f32_e32 v142, v66
	v_exp_f32_e32 v143, v67
	v_exp_f32_e32 v144, v68
	v_exp_f32_e32 v145, v69
	v_exp_f32_e32 v147, v70
	v_exp_f32_e32 v148, v71
	v_exp_f32_e32 v149, v72
	v_exp_f32_e32 v150, v73
	s_waitcnt lgkmcnt(1)
	v_mfma_f32_32x32x16_bf16 v[82:97], v[244:247], v[158:161], v[34:49]
	v_exp_f32_e32 v151, v74
	v_exp_f32_e32 v152, v75
	v_exp_f32_e32 v153, v76
	v_exp_f32_e32 v178, v77
	v_exp_f32_e32 v134, v78
	v_exp_f32_e32 v135, v79
	v_exp_f32_e32 v136, v80
	v_exp_f32_e32 v137, v81
	v_mfma_f32_32x32x16_bf16 v[98:113], v[130:133], v[154:157], v[98:113]
	v_exp_f32_e32 v179, v50
	v_exp_f32_e32 v185, v51
	v_exp_f32_e32 v186, v52
	v_exp_f32_e32 v187, v53
	v_exp_f32_e32 v194, v54
	v_exp_f32_e32 v195, v55
	v_exp_f32_e32 v196, v56
	v_exp_f32_e32 v197, v57
	s_waitcnt lgkmcnt(0)
	v_mfma_f32_32x32x16_bf16 v[82:97], v[138:141], v[154:157], v[82:97]
	v_exp_f32_e32 v198, v58
	v_exp_f32_e32 v199, v59
	v_exp_f32_e32 v200, v60
	v_exp_f32_e32 v201, v61
	v_exp_f32_e32 v138, v62
	v_exp_f32_e32 v139, v63
	v_exp_f32_e32 v140, v64
	v_exp_f32_e32 v141, v65
	s_cmp_gt_i32 s24, 2
	s_cselect_b32 s25, -3, 2
	s_add_i32 s25, s25, s24
	s_mulk_i32 s25, 0x2400
	v_add_u32_e32 v50, s25, v182
	s_add_i32 s25, s24, 1
	s_cmp_lg_u32 s24, 4
	s_cselect_b32 s25, s25, 0
	s_add_i32 s24, s23, -3
	s_min_u32 s26, s24, s13
	s_lshl_b32 s92, s26, 13
	s_waitcnt vmcnt(3)
	ds_write_b128 v182, v[118:121] offset:27648
	s_waitcnt vmcnt(2)
	ds_write_b128 v50, v[114:117] offset:36864
	s_add_u32 vcc_lo, s100, s92
	s_addc_u32 vcc_hi, s101, 0
	global_load_dwordx4 v[118:121], v248, vcc
	s_add_i32 s92, s23, -4
	s_lshl_b32 s92, s92, 7
	s_add_u32 vcc_lo, s98, s92
	s_addc_u32 vcc_hi, s99, 0
	global_load_dwordx4 v[114:117], v249, vcc
	s_mul_i32 s27, s25, 0x2400
	s_add_i32 s28, s27, 0xffffdc00
	s_cmp_lg_u32 s25, 0
	s_cselect_b32 s28, s28, 0x9000
	v_add_u32_e32 v78, s28, v163
	ds_read_b128 v[50:53], v78 offset:36864
	ds_read_b128 v[54:57], v78 offset:36896
	ds_read_b128 v[58:61], v78 offset:41472
	ds_read_b128 v[62:65], v78 offset:41504
	ds_read_b128 v[66:69], v78 offset:36928
	ds_read_b128 v[70:73], v78 offset:36960
	ds_read_b128 v[74:77], v78 offset:41536
	ds_read_b128 v[78:81], v78 offset:41568
	s_setprio 3
	v_cvt_pk_bf16_f32 v130, v142, v143
	v_cvt_pk_bf16_f32 v131, v144, v145
	v_cvt_pk_bf16_f32 v132, v147, v148
	v_cvt_pk_bf16_f32 v133, v149, v150
	s_waitcnt lgkmcnt(7)
	s_nop 0
	v_mfma_f32_32x32x16_bf16 v[18:33], v[50:53], v[130:133], v[18:33]
	v_add_f32_e32 v176, v142, v143
	v_add_f32_e32 v176, v176, v144
	v_add_f32_e32 v176, v176, v145
	s_waitcnt lgkmcnt(5)
	v_mfma_f32_32x32x16_bf16 v[2:17], v[58:61], v[130:133], v[2:17]
	v_cvt_pk_bf16_f32 v50, v151, v152
	v_cvt_pk_bf16_f32 v51, v153, v178
	v_cvt_pk_bf16_f32 v52, v134, v135
	v_cvt_pk_bf16_f32 v53, v136, v137
	v_add_f32_e32 v176, v176, v147
	v_add_f32_e32 v176, v176, v148
	v_add_f32_e32 v176, v176, v149
	v_add_f32_e32 v176, v176, v150
	s_nop 0
	v_mfma_f32_32x32x16_bf16 v[18:33], v[54:57], v[50:53], v[18:33]
	v_add_f32_e32 v176, v176, v151
	v_add_f32_e32 v176, v176, v152
	v_add_f32_e32 v176, v176, v153
	v_add_f32_e32 v176, v176, v178
	s_waitcnt lgkmcnt(4)
	v_mfma_f32_32x32x16_bf16 v[2:17], v[62:65], v[50:53], v[2:17]
	v_cvt_pk_bf16_f32 v54, v179, v185
	v_cvt_pk_bf16_f32 v55, v186, v187
	v_cvt_pk_bf16_f32 v56, v194, v195
	v_cvt_pk_bf16_f32 v57, v196, v197
	v_add_f32_e32 v176, v176, v134
	v_add_f32_e32 v176, v176, v135
	v_add_f32_e32 v176, v176, v136
	v_add_f32_e32 v176, v176, v137
	s_waitcnt lgkmcnt(3)
	v_mfma_f32_32x32x16_bf16 v[18:33], v[66:69], v[54:57], v[18:33]
	v_add_f32_e32 v176, v176, v179
	v_add_f32_e32 v176, v176, v185
	v_add_f32_e32 v176, v176, v186
	v_add_f32_e32 v176, v176, v187
	s_waitcnt lgkmcnt(1)
	v_mfma_f32_32x32x16_bf16 v[2:17], v[74:77], v[54:57], v[2:17]
	v_cvt_pk_bf16_f32 v50, v198, v199
	v_cvt_pk_bf16_f32 v51, v200, v201
	v_cvt_pk_bf16_f32 v52, v138, v139
	v_cvt_pk_bf16_f32 v53, v140, v141
	v_add_f32_e32 v176, v176, v194
	v_add_f32_e32 v176, v176, v195
	v_add_f32_e32 v176, v176, v196
	v_add_f32_e32 v176, v176, v197
	s_nop 0
	v_mfma_f32_32x32x16_bf16 v[18:33], v[70:73], v[50:53], v[18:33]
	v_add_f32_e32 v176, v176, v198
	v_add_f32_e32 v176, v176, v199
	v_add_f32_e32 v176, v176, v200
	v_add_f32_e32 v176, v176, v201
	s_waitcnt lgkmcnt(0)
	v_mfma_f32_32x32x16_bf16 v[2:17], v[78:81], v[50:53], v[2:17]
	v_add_f32_e32 v176, v176, v138
	v_add_f32_e32 v176, v176, v139
	v_add_f32_e32 v176, v176, v140
	v_add_f32_e32 v176, v176, v141
	s_setprio 2
	s_waitcnt lgkmcnt(0)
	s_barrier
	ds_read_b128 v[240:243], v165 offset:18432
	ds_read_b128 v[244:247], v165 offset:23040
	ds_read_b128 v[134:137], v165 offset:18464
	ds_read_b128 v[138:141], v165 offset:23072
	v_add_f32_e32 v1, v1, v146
	v_exp_f32_e32 v142, v98
	v_exp_f32_e32 v143, v99
	v_exp_f32_e32 v144, v100
	v_exp_f32_e32 v145, v101
	v_exp_f32_e32 v146, v102
	v_exp_f32_e32 v147, v103
	v_exp_f32_e32 v148, v104
	v_exp_f32_e32 v149, v105
	v_exp_f32_e32 v150, v106
	v_exp_f32_e32 v151, v107
	v_exp_f32_e32 v152, v108
	v_exp_f32_e32 v153, v109
	s_waitcnt lgkmcnt(2)
	v_mfma_f32_32x32x16_bf16 v[66:81], v[240:243], v[158:161], v[34:49]
	v_mfma_f32_32x32x16_bf16 v[50:65], v[244:247], v[158:161], v[34:49]
	v_exp_f32_e32 v177, v110
	v_exp_f32_e32 v178, v111
	v_exp_f32_e32 v179, v112
	v_exp_f32_e32 v185, v113
	s_waitcnt lgkmcnt(1)
	v_mfma_f32_32x32x16_bf16 v[66:81], v[134:137], v[154:157], v[66:81]
	v_exp_f32_e32 v186, v82
	v_exp_f32_e32 v187, v83
	v_exp_f32_e32 v194, v84
	v_exp_f32_e32 v195, v85
	v_exp_f32_e32 v134, v86
	v_exp_f32_e32 v135, v87
	v_exp_f32_e32 v136, v88
	v_exp_f32_e32 v137, v89
	s_waitcnt lgkmcnt(0)
	v_mfma_f32_32x32x16_bf16 v[50:65], v[138:141], v[154:157], v[50:65]
	v_exp_f32_e32 v196, v90
	v_exp_f32_e32 v197, v91
	v_exp_f32_e32 v198, v92
	v_exp_f32_e32 v199, v93
	v_exp_f32_e32 v138, v94
	v_exp_f32_e32 v139, v95
	v_exp_f32_e32 v140, v96
	v_exp_f32_e32 v141, v97
	s_cmp_gt_i32 s25, 2
	s_cselect_b32 s28, -3, 2
	s_waitcnt vmcnt(3)
	ds_write_b128 v182, v[126:129]
	s_add_i32 s28, s28, s25
	v_add_u32_e32 v126, s27, v163
	s_add_i32 s27, s23, -2
	s_mulk_i32 s28, 0x2400
	s_min_u32 s27, s27, s13
	v_add_u32_e32 v82, s28, v182
	s_lshl_b32 s92, s27, 13
	s_waitcnt vmcnt(2)
	ds_write_b128 v82, v[122:125] offset:36864
	ds_read_b128 v[240:243], v165 offset:27648
	ds_read_b128 v[244:247], v165 offset:32256
	ds_read_b128 v[82:85], v126 offset:41472
	ds_read_b128 v[86:89], v126 offset:36864
	ds_read_b128 v[90:93], v126 offset:36896
	ds_read_b128 v[94:97], v126 offset:41504
	ds_read_b128 v[106:109], v126 offset:36928
	ds_read_b128 v[110:113], v126 offset:41536
	ds_read_b128 v[122:125], v126 offset:36960
	ds_read_b128 v[126:129], v126 offset:41568
	s_add_u32 vcc_lo, s100, s92
	s_addc_u32 vcc_hi, s101, 0
	global_load_dwordx4 v[98:101], v248, vcc
	s_lshl_b32 s92, s26, 7
	s_add_u32 vcc_lo, s98, s92
	s_addc_u32 vcc_hi, s99, 0
	global_load_dwordx4 v[102:105], v249, vcc
	v_add_f32_e32 v1, v1, v176
	s_add_i32 s28, s25, 1
	s_setprio 1
	v_cvt_pk_bf16_f32 v130, v142, v143
	v_cvt_pk_bf16_f32 v131, v144, v145
	v_cvt_pk_bf16_f32 v132, v146, v147
	v_cvt_pk_bf16_f32 v133, v148, v149
	s_waitcnt lgkmcnt(6)
	s_nop 0
	v_mfma_f32_32x32x16_bf16 v[18:33], v[86:89], v[130:133], v[18:33]
	v_add_f32_e32 v176, v142, v143
	v_add_f32_e32 v176, v176, v144
	v_add_f32_e32 v176, v176, v145
	s_nop 0
	v_mfma_f32_32x32x16_bf16 v[2:17], v[82:85], v[130:133], v[2:17]
	v_cvt_pk_bf16_f32 v86, v150, v151
	v_cvt_pk_bf16_f32 v87, v152, v153
	v_cvt_pk_bf16_f32 v88, v177, v178
	v_cvt_pk_bf16_f32 v89, v179, v185
	v_add_f32_e32 v176, v176, v146
	v_add_f32_e32 v176, v176, v147
	v_add_f32_e32 v176, v176, v148
	v_add_f32_e32 v176, v176, v149
	s_waitcnt lgkmcnt(5)
	v_mfma_f32_32x32x16_bf16 v[18:33], v[90:93], v[86:89], v[18:33]
	v_add_f32_e32 v176, v176, v150
	v_add_f32_e32 v176, v176, v151
	v_add_f32_e32 v176, v176, v152
	v_add_f32_e32 v176, v176, v153
	s_waitcnt lgkmcnt(4)
	v_mfma_f32_32x32x16_bf16 v[2:17], v[94:97], v[86:89], v[2:17]
	v_cvt_pk_bf16_f32 v82, v186, v187
	v_cvt_pk_bf16_f32 v83, v194, v195
	v_cvt_pk_bf16_f32 v84, v134, v135
	v_cvt_pk_bf16_f32 v85, v136, v137
	v_add_f32_e32 v176, v176, v177
	v_add_f32_e32 v176, v176, v178
	v_add_f32_e32 v176, v176, v179
	v_add_f32_e32 v176, v176, v185
	s_waitcnt lgkmcnt(3)
	v_mfma_f32_32x32x16_bf16 v[18:33], v[106:109], v[82:85], v[18:33]
	v_add_f32_e32 v176, v176, v186
	v_add_f32_e32 v176, v176, v187
	v_add_f32_e32 v176, v176, v194
	v_add_f32_e32 v176, v176, v195
	s_waitcnt lgkmcnt(2)
	v_mfma_f32_32x32x16_bf16 v[2:17], v[110:113], v[82:85], v[2:17]
	v_cvt_pk_bf16_f32 v86, v196, v197
	v_cvt_pk_bf16_f32 v87, v198, v199
	v_cvt_pk_bf16_f32 v88, v138, v139
	v_cvt_pk_bf16_f32 v89, v140, v141
	v_add_f32_e32 v176, v176, v134
	v_add_f32_e32 v176, v176, v135
	v_add_f32_e32 v176, v176, v136
	v_add_f32_e32 v176, v176, v137
	s_waitcnt lgkmcnt(1)
	v_mfma_f32_32x32x16_bf16 v[18:33], v[122:125], v[86:89], v[18:33]
	v_add_f32_e32 v176, v176, v196
	v_add_f32_e32 v176, v176, v197
	v_add_f32_e32 v176, v176, v198
	v_add_f32_e32 v176, v176, v199
	s_waitcnt lgkmcnt(0)
	v_mfma_f32_32x32x16_bf16 v[2:17], v[126:129], v[86:89], v[2:17]
	v_add_f32_e32 v176, v176, v138
	v_add_f32_e32 v176, v176, v139
	v_add_f32_e32 v176, v176, v140
	v_add_f32_e32 v176, v176, v141
	s_setprio 0
	ds_read_b128 v[106:109], v165 offset:27680
	ds_read_b128 v[122:125], v165 offset:32288
	s_cmp_lg_u32 s25, 4
	s_cselect_b32 s25, s28, 0
	s_waitcnt lgkmcnt(2)
	v_mfma_f32_32x32x16_bf16 v[138:153], v[240:243], v[158:161], v[34:49]
	v_exp_f32_e32 v126, v66
	v_exp_f32_e32 v127, v67
	v_exp_f32_e32 v128, v68
	v_exp_f32_e32 v129, v69
	v_exp_f32_e32 v130, v70
	v_exp_f32_e32 v131, v71
	v_exp_f32_e32 v132, v72
	v_exp_f32_e32 v133, v73
	s_waitcnt lgkmcnt(1)
	v_mfma_f32_32x32x16_bf16 v[82:97], v[244:247], v[158:161], v[34:49]
	v_exp_f32_e32 v134, v74
	v_exp_f32_e32 v135, v75
	v_exp_f32_e32 v136, v76
	v_exp_f32_e32 v137, v77
	v_exp_f32_e32 v177, v78
	v_exp_f32_e32 v178, v79
	v_exp_f32_e32 v179, v80
	v_exp_f32_e32 v185, v81
	v_mfma_f32_32x32x16_bf16 v[138:153], v[106:109], v[154:157], v[138:153]
	v_exp_f32_e32 v80, v50
	v_exp_f32_e32 v81, v51
	v_exp_f32_e32 v186, v52
	v_exp_f32_e32 v187, v53
	v_exp_f32_e32 v194, v54
	v_exp_f32_e32 v195, v55
	v_exp_f32_e32 v196, v56
	v_exp_f32_e32 v197, v57
	s_waitcnt lgkmcnt(0)
	v_mfma_f32_32x32x16_bf16 v[82:97], v[122:125], v[154:157], v[82:97]
	v_exp_f32_e32 v198, v58
	v_exp_f32_e32 v199, v59
	v_exp_f32_e32 v200, v60
	v_exp_f32_e32 v201, v61
	v_exp_f32_e32 v122, v62
	v_exp_f32_e32 v123, v63
	v_exp_f32_e32 v124, v64
	v_exp_f32_e32 v125, v65
	s_cmp_gt_i32 s25, 2
	s_cselect_b32 s26, -3, 2
	s_add_i32 s26, s26, s25
	s_mulk_i32 s26, 0x2400
	v_add_u32_e32 v50, s26, v182
	s_add_i32 s26, s25, 1
	s_cmp_lg_u32 s25, 4
	s_cselect_b32 s25, s26, 0
	s_add_i32 s26, s23, -1
	s_min_u32 s26, s26, s13
	s_lshl_b32 s92, s26, 13
	s_waitcnt vmcnt(3)
	ds_write_b128 v182, v[118:121] offset:9216
	s_waitcnt vmcnt(2)
	ds_write_b128 v50, v[114:117] offset:36864
	s_add_u32 vcc_lo, s100, s92
	s_addc_u32 vcc_hi, s101, 0
	global_load_dwordx4 v[56:59], v248, vcc
	s_lshl_b32 s92, s27, 7
	s_add_u32 vcc_lo, s98, s92
	s_addc_u32 vcc_hi, s99, 0
	global_load_dwordx4 v[52:55], v249, vcc
	s_nop 0
	s_mul_i32 s27, s25, 0x2400
	s_add_i32 s28, s27, 0xffffdc00
	s_cmp_lg_u32 s25, 0
	s_cselect_b32 s28, s28, 0x9000
	v_add_u32_e32 v50, s28, v163
	ds_read_b128 v[60:63], v50 offset:36864
	ds_read_b128 v[64:67], v50 offset:36896
	ds_read_b128 v[68:71], v50 offset:41472
	ds_read_b128 v[72:75], v50 offset:41504
	ds_read_b128 v[76:79], v50 offset:36928
	ds_read_b128 v[106:109], v50 offset:36960
	ds_read_b128 v[110:113], v50 offset:41536
	ds_read_b128 v[114:117], v50 offset:41568
	s_setprio 3
	v_cvt_pk_bf16_f32 v118, v126, v127
	v_cvt_pk_bf16_f32 v119, v128, v129
	v_cvt_pk_bf16_f32 v120, v130, v131
	v_cvt_pk_bf16_f32 v121, v132, v133
	s_waitcnt lgkmcnt(7)
	s_nop 0
	v_mfma_f32_32x32x16_bf16 v[18:33], v[60:63], v[118:121], v[18:33]
	v_add_f32_e32 v50, v126, v127
	v_add_f32_e32 v50, v50, v128
	v_add_f32_e32 v50, v50, v129
	s_waitcnt lgkmcnt(5)
	v_mfma_f32_32x32x16_bf16 v[2:17], v[68:71], v[118:121], v[2:17]
	v_cvt_pk_bf16_f32 v60, v134, v135
	v_cvt_pk_bf16_f32 v61, v136, v137
	v_cvt_pk_bf16_f32 v62, v177, v178
	v_cvt_pk_bf16_f32 v63, v179, v185
	v_add_f32_e32 v50, v50, v130
	v_add_f32_e32 v50, v50, v131
	v_add_f32_e32 v50, v50, v132
	v_add_f32_e32 v50, v50, v133
	s_nop 0
	v_mfma_f32_32x32x16_bf16 v[18:33], v[64:67], v[60:63], v[18:33]
	v_add_f32_e32 v50, v50, v134
	v_add_f32_e32 v50, v50, v135
	v_add_f32_e32 v50, v50, v136
	v_add_f32_e32 v50, v50, v137
	s_waitcnt lgkmcnt(4)
	v_mfma_f32_32x32x16_bf16 v[2:17], v[72:75], v[60:63], v[2:17]
	v_cvt_pk_bf16_f32 v64, v80, v81
	v_cvt_pk_bf16_f32 v65, v186, v187
	v_cvt_pk_bf16_f32 v66, v194, v195
	v_cvt_pk_bf16_f32 v67, v196, v197
	v_add_f32_e32 v50, v50, v177
	v_add_f32_e32 v50, v50, v178
	v_add_f32_e32 v50, v50, v179
	v_add_f32_e32 v50, v50, v185
	s_waitcnt lgkmcnt(3)
	v_mfma_f32_32x32x16_bf16 v[18:33], v[76:79], v[64:67], v[18:33]
	v_add_f32_e32 v50, v50, v80
	v_add_f32_e32 v50, v50, v81
	v_add_f32_e32 v50, v50, v186
	v_add_f32_e32 v50, v50, v187
	s_waitcnt lgkmcnt(1)
	v_mfma_f32_32x32x16_bf16 v[2:17], v[110:113], v[64:67], v[2:17]
	v_cvt_pk_bf16_f32 v60, v198, v199
	v_cvt_pk_bf16_f32 v61, v200, v201
	v_cvt_pk_bf16_f32 v62, v122, v123
	v_cvt_pk_bf16_f32 v63, v124, v125
	v_add_f32_e32 v50, v50, v194
	v_add_f32_e32 v50, v50, v195
	v_add_f32_e32 v50, v50, v196
	v_add_f32_e32 v50, v50, v197
	s_nop 0
	v_mfma_f32_32x32x16_bf16 v[18:33], v[106:109], v[60:63], v[18:33]
	v_add_f32_e32 v50, v50, v198
	v_add_f32_e32 v50, v50, v199
	v_add_f32_e32 v50, v50, v200
	v_add_f32_e32 v50, v50, v201
	s_waitcnt lgkmcnt(0)
	v_mfma_f32_32x32x16_bf16 v[2:17], v[114:117], v[60:63], v[2:17]
	v_add_f32_e32 v50, v50, v122
	v_add_f32_e32 v50, v50, v123
	v_add_f32_e32 v50, v50, v124
	v_add_f32_e32 v50, v50, v125
	s_setprio 2
	s_waitcnt lgkmcnt(0)
	s_barrier
	ds_read_b128 v[240:243], v165
	ds_read_b128 v[244:247], v165 offset:4608
	ds_read_b128 v[68:71], v165 offset:32
	ds_read_b128 v[72:75], v165 offset:4640
	v_add_f32_e32 v1, v1, v176
	v_exp_f32_e32 v176, v138
	v_exp_f32_e32 v177, v139
	v_exp_f32_e32 v178, v140
	v_exp_f32_e32 v179, v141
	v_exp_f32_e32 v185, v142
	v_exp_f32_e32 v186, v143
	v_exp_f32_e32 v187, v144
	v_exp_f32_e32 v194, v145
	v_exp_f32_e32 v195, v146
	v_exp_f32_e32 v196, v147
	v_exp_f32_e32 v197, v148
	v_exp_f32_e32 v198, v149
	s_waitcnt lgkmcnt(2)
	v_mfma_f32_32x32x16_bf16 v[122:137], v[240:243], v[158:161], v[34:49]
	v_mfma_f32_32x32x16_bf16 v[106:121], v[244:247], v[158:161], v[34:49]
	v_exp_f32_e32 v146, v150
	v_exp_f32_e32 v147, v151
	v_exp_f32_e32 v148, v152
	v_exp_f32_e32 v149, v153
	s_waitcnt lgkmcnt(1)
	v_mfma_f32_32x32x16_bf16 v[122:137], v[68:71], v[154:157], v[122:137]
	v_exp_f32_e32 v150, v82
	v_exp_f32_e32 v151, v83
	v_exp_f32_e32 v152, v84
	v_exp_f32_e32 v153, v85
	v_exp_f32_e32 v199, v86
	v_exp_f32_e32 v200, v87
	v_exp_f32_e32 v201, v88
	v_exp_f32_e32 v202, v89
	s_waitcnt lgkmcnt(0)
	v_mfma_f32_32x32x16_bf16 v[106:121], v[72:75], v[154:157], v[106:121]
	v_exp_f32_e32 v203, v90
	v_exp_f32_e32 v204, v91
	v_exp_f32_e32 v205, v92
	v_exp_f32_e32 v206, v93
	v_exp_f32_e32 v207, v94
	v_exp_f32_e32 v208, v95
	v_exp_f32_e32 v209, v96
	v_exp_f32_e32 v210, v97
	v_add_u32_e32 v88, s27, v163
	ds_read_b128 v[240:243], v165 offset:9216
	ds_read_b128 v[244:247], v165 offset:13824
	ds_read_b128 v[60:63], v88 offset:41472
	ds_read_b128 v[64:67], v88 offset:36864
	ds_read_b128 v[68:71], v88 offset:36896
	ds_read_b128 v[72:75], v88 offset:41504
	ds_read_b128 v[76:79], v88 offset:36928
	ds_read_b128 v[80:83], v88 offset:41536
	ds_read_b128 v[84:87], v88 offset:36960
	ds_read_b128 v[88:91], v88 offset:41568
	s_cmp_gt_i32 s25, 2
	s_cselect_b32 s28, -3, 2
	s_add_i32 s28, s28, s25
	s_mulk_i32 s28, 0x2400
	s_min_u32 s27, s23, s13
	v_add_u32_e32 v51, s28, v182
	s_lshl_b32 s92, s27, 13
	s_waitcnt vmcnt(3)
	ds_write_b128 v182, v[98:101] offset:18432
	s_waitcnt vmcnt(2)
	ds_write_b128 v51, v[102:105] offset:36864
	v_add_f32_e32 v1, v1, v50
	s_add_u32 vcc_lo, s100, s92
	s_addc_u32 vcc_hi, s101, 0
	global_load_dwordx4 v[138:141], v248, vcc
	s_lshl_b32 s92, s26, 7
	s_add_u32 vcc_lo, s98, s92
	s_addc_u32 vcc_hi, s99, 0
	global_load_dwordx4 v[142:145], v249, vcc
	s_setprio 1
	v_mov_b32_e32 v51, v122
	v_cvt_pk_bf16_f32 v92, v176, v177
	v_cvt_pk_bf16_f32 v93, v178, v179
	v_cvt_pk_bf16_f32 v94, v185, v186
	v_cvt_pk_bf16_f32 v95, v187, v194
	s_waitcnt lgkmcnt(8)
	s_nop 0
	v_mfma_f32_32x32x16_bf16 v[18:33], v[64:67], v[92:95], v[18:33]
	v_max3_f32 v51, v51, v123, v124
	v_max3_f32 v51, v51, v125, v126
	v_add_f32_e32 v50, v176, v177
	v_add_f32_e32 v50, v50, v178
	v_add_f32_e32 v50, v50, v179
	s_nop 0
	v_mfma_f32_32x32x16_bf16 v[2:17], v[60:63], v[92:95], v[2:17]
	v_cvt_pk_bf16_f32 v64, v195, v196
	v_cvt_pk_bf16_f32 v65, v197, v198
	v_cvt_pk_bf16_f32 v66, v146, v147
	v_cvt_pk_bf16_f32 v67, v148, v149
	v_max3_f32 v51, v51, v127, v128
	v_max3_f32 v51, v51, v129, v130
	v_add_f32_e32 v50, v50, v185
	v_add_f32_e32 v50, v50, v186
	v_add_f32_e32 v50, v50, v187
	v_add_f32_e32 v50, v50, v194
	s_waitcnt lgkmcnt(7)
	v_mfma_f32_32x32x16_bf16 v[18:33], v[68:71], v[64:67], v[18:33]
	v_max3_f32 v51, v51, v131, v132
	v_max3_f32 v51, v51, v133, v134
	v_add_f32_e32 v50, v50, v195
	v_add_f32_e32 v50, v50, v196
	v_add_f32_e32 v50, v50, v197
	v_add_f32_e32 v50, v50, v198
	s_waitcnt lgkmcnt(6)
	v_mfma_f32_32x32x16_bf16 v[2:17], v[72:75], v[64:67], v[2:17]
	v_cvt_pk_bf16_f32 v60, v150, v151
	v_cvt_pk_bf16_f32 v61, v152, v153
	v_cvt_pk_bf16_f32 v62, v199, v200
	v_cvt_pk_bf16_f32 v63, v201, v202
	v_max3_f32 v51, v51, v135, v136
	v_max3_f32 v51, v51, v137, v106
	v_add_f32_e32 v50, v50, v146
	v_add_f32_e32 v50, v50, v147
	v_add_f32_e32 v50, v50, v148
	v_add_f32_e32 v50, v50, v149
	s_waitcnt lgkmcnt(5)
	v_mfma_f32_32x32x16_bf16 v[18:33], v[76:79], v[60:63], v[18:33]
	v_max3_f32 v51, v51, v107, v108
	v_max3_f32 v51, v51, v109, v110
	v_add_f32_e32 v50, v50, v150
	v_add_f32_e32 v50, v50, v151
	v_add_f32_e32 v50, v50, v152
	v_add_f32_e32 v50, v50, v153
	s_waitcnt lgkmcnt(4)
	v_mfma_f32_32x32x16_bf16 v[2:17], v[80:83], v[60:63], v[2:17]
	v_cvt_pk_bf16_f32 v64, v203, v204
	v_cvt_pk_bf16_f32 v65, v205, v206
	v_cvt_pk_bf16_f32 v66, v207, v208
	v_cvt_pk_bf16_f32 v67, v209, v210
	v_max3_f32 v51, v51, v111, v112
	v_max3_f32 v51, v51, v113, v114
	v_add_f32_e32 v50, v50, v199
	v_add_f32_e32 v50, v50, v200
	v_add_f32_e32 v50, v50, v201
	v_add_f32_e32 v50, v50, v202
	s_waitcnt lgkmcnt(3)
	v_mfma_f32_32x32x16_bf16 v[18:33], v[84:87], v[64:67], v[18:33]
	v_max3_f32 v51, v51, v115, v116
	v_max3_f32 v51, v51, v117, v118
	v_add_f32_e32 v50, v50, v203
	v_add_f32_e32 v50, v50, v204
	v_add_f32_e32 v50, v50, v205
	v_add_f32_e32 v50, v50, v206
	s_waitcnt lgkmcnt(2)
	v_mfma_f32_32x32x16_bf16 v[2:17], v[88:91], v[64:67], v[2:17]
	v_max3_f32 v51, v51, v119, v120
	v_max3_f32 v51, v51, v121, v121
	v_add_f32_e32 v50, v50, v207
	v_add_f32_e32 v50, v50, v208
	v_add_f32_e32 v50, v50, v209
	v_add_f32_e32 v50, v50, v210
	s_setprio 0
	ds_read_b128 v[146:149], v165 offset:9248
	ds_read_b128 v[60:63], v165 offset:13856
	v_add_f32_e32 v50, v1, v50
	v_mov_b32_e32 v1, v51
	s_nop 1
	v_permlane32_swap_b32_e32 v51, v1
	v_max_f32_e32 v1, v1, v1
	v_max_f32_e32 v51, v51, v51
	v_max_f32_e32 v1, v51, v1
	v_cmp_lt_f32_e32 vcc, s52, v1
	s_cbranch_vccz .LBB0_643
	v_max_f32_e32 v1, v1, v1
	v_max_f32_e32 v68, 0, v1
	v_add_f32_e32 v183, v183, v68
	v_xor_b32_e32 v34, 0x80000000, v183
	v_pk_add_f32 v[122:123], v[122:123], v[68:69] op_sel_hi:[1,0] neg_lo:[0,1] neg_hi:[0,1]
	v_pk_add_f32 v[106:107], v[106:107], v[68:69] op_sel_hi:[1,0] neg_lo:[0,1] neg_hi:[0,1]
	v_pk_add_f32 v[124:125], v[124:125], v[68:69] op_sel_hi:[1,0] neg_lo:[0,1] neg_hi:[0,1]
	v_pk_add_f32 v[108:109], v[108:109], v[68:69] op_sel_hi:[1,0] neg_lo:[0,1] neg_hi:[0,1]
	v_pk_add_f32 v[126:127], v[126:127], v[68:69] op_sel_hi:[1,0] neg_lo:[0,1] neg_hi:[0,1]
	v_pk_add_f32 v[110:111], v[110:111], v[68:69] op_sel_hi:[1,0] neg_lo:[0,1] neg_hi:[0,1]
	v_pk_add_f32 v[128:129], v[128:129], v[68:69] op_sel_hi:[1,0] neg_lo:[0,1] neg_hi:[0,1]
	v_pk_add_f32 v[112:113], v[112:113], v[68:69] op_sel_hi:[1,0] neg_lo:[0,1] neg_hi:[0,1]
	v_pk_add_f32 v[130:131], v[130:131], v[68:69] op_sel_hi:[1,0] neg_lo:[0,1] neg_hi:[0,1]
	v_pk_add_f32 v[114:115], v[114:115], v[68:69] op_sel_hi:[1,0] neg_lo:[0,1] neg_hi:[0,1]
	v_pk_add_f32 v[132:133], v[132:133], v[68:69] op_sel_hi:[1,0] neg_lo:[0,1] neg_hi:[0,1]
	v_pk_add_f32 v[116:117], v[116:117], v[68:69] op_sel_hi:[1,0] neg_lo:[0,1] neg_hi:[0,1]
	v_pk_add_f32 v[134:135], v[134:135], v[68:69] op_sel_hi:[1,0] neg_lo:[0,1] neg_hi:[0,1]
	v_pk_add_f32 v[118:119], v[118:119], v[68:69] op_sel_hi:[1,0] neg_lo:[0,1] neg_hi:[0,1]
	v_pk_add_f32 v[136:137], v[136:137], v[68:69] op_sel_hi:[1,0] neg_lo:[0,1] neg_hi:[0,1]
	v_pk_add_f32 v[120:121], v[120:121], v[68:69] op_sel_hi:[1,0] neg_lo:[0,1] neg_hi:[0,1]
	v_exp_f32_e64 v68, -v68
	v_mov_b32_e32 v35, v34
	v_mov_b32_e32 v36, v34
	v_mov_b32_e32 v37, v34
	v_mov_b32_e32 v38, v34
	v_mov_b32_e32 v39, v34
	v_mov_b32_e32 v40, v34
	v_mov_b32_e32 v41, v34
	v_mov_b32_e32 v42, v34
	v_mov_b32_e32 v43, v34
	v_mov_b32_e32 v44, v34
	v_mov_b32_e32 v45, v34
	v_mov_b32_e32 v46, v34
	v_mov_b32_e32 v47, v34
	v_mov_b32_e32 v48, v34
	v_mov_b32_e32 v49, v34
	s_nop 11
	v_pk_mul_f32 v[32:33], v[32:33], v[68:69] op_sel_hi:[1,0]
	v_pk_mul_f32 v[30:31], v[30:31], v[68:69] op_sel_hi:[1,0]
	v_pk_mul_f32 v[28:29], v[28:29], v[68:69] op_sel_hi:[1,0]
	v_pk_mul_f32 v[26:27], v[26:27], v[68:69] op_sel_hi:[1,0]
	v_pk_mul_f32 v[24:25], v[24:25], v[68:69] op_sel_hi:[1,0]
	v_pk_mul_f32 v[22:23], v[22:23], v[68:69] op_sel_hi:[1,0]
	v_pk_mul_f32 v[20:21], v[20:21], v[68:69] op_sel_hi:[1,0]
	v_pk_mul_f32 v[18:19], v[18:19], v[68:69] op_sel_hi:[1,0]
	v_pk_mul_f32 v[16:17], v[16:17], v[68:69] op_sel_hi:[1,0]
	v_pk_mul_f32 v[14:15], v[14:15], v[68:69] op_sel_hi:[1,0]
	v_pk_mul_f32 v[12:13], v[12:13], v[68:69] op_sel_hi:[1,0]
	v_pk_mul_f32 v[10:11], v[10:11], v[68:69] op_sel_hi:[1,0]
	v_pk_mul_f32 v[8:9], v[8:9], v[68:69] op_sel_hi:[1,0]
	v_pk_mul_f32 v[6:7], v[6:7], v[68:69] op_sel_hi:[1,0]
	v_pk_mul_f32 v[4:5], v[4:5], v[68:69] op_sel_hi:[1,0]
	v_pk_mul_f32 v[2:3], v[2:3], v[68:69] op_sel_hi:[1,0]
	v_mul_f32_e32 v50, v50, v68
